# cv32 + T1 thin_rows loop: the countdown vmcnt ladder (which also waited for the just-issued prefetch of the next row) replaced by counted waits at the head of each half (vmcnt(8): only the >=8 younger
# speedup vs baseline: 1.0077x; 1.0019x over previous
.LBB0_1573:
	s_cmp_le_i32 s62, s6
	s_cselect_b64 s[0:1], -1, 0
	s_cmp_lt_i32 s6, s63
	s_cselect_b64 s[4:5], -1, 0
	s_and_b64 s[0:1], s[0:1], s[4:5]
	s_andn2_b64 vcc, exec, s[0:1]
	s_cbranch_vccnz .LBB0_1602
	v_readlane_b32 s4, v253, 3
	v_readlane_b32 s5, v253, 4
	s_waitcnt lgkmcnt(0)
	s_load_dwordx2 s[8:9], s[4:5], 0x90
	s_nop 0
	s_load_dwordx2 s[4:5], s[4:5], 0xc0
	v_mov_b32_e32 v17, v0
	s_waitcnt lgkmcnt(0)
	v_readlane_b32 s10, v253, 53
	v_readfirstlane_b32 s6, v17
	s_ashr_i32 s6, s6, 6
	s_lshl_b32 s20, s30, 11
	s_add_i32 s12, s6, s10
	s_lshl_b64 s[10:11], s[20:21], 2
	s_add_u32 s8, s8, s10
	s_waitcnt vmcnt(0)
	v_and_b32_e32 v118, 63, v17
	s_addc_u32 s9, s9, s11
	s_cmpk_gt_i32 s12, 0x1fff
	v_cmp_eq_u32_e64 s[42:43], 0, v118
	s_cbranch_scc1 .LBB0_1587
	s_add_u32 s10, s4, 0x20d00000
	s_addc_u32 s11, s5, 0
	s_add_u32 s6, s4, 0x47800000
	s_addc_u32 s14, s5, 0
	s_add_u32 s16, s4, 0x39400000
	s_addc_u32 s17, s5, 0
	s_ashr_i32 s13, s12, 31
	s_lshl_b64 s[26:27], s[12:13], 12
	v_lshlrev_b32_e32 v14, 4, v118
	s_add_u32 s28, s16, s26
	v_or_b32_e32 v15, 0x1000, v14
	v_or_b32_e32 v26, 0x1400, v14
	s_addc_u32 s29, s17, s27
	global_load_dwordx4 v[2:5], v14, s[8:9]
	global_load_dwordx4 v[6:9], v14, s[8:9] offset:1024
	global_load_dwordx4 v[10:13], v14, s[8:9] offset:2048
	global_load_dwordx4 v[18:21], v14, s[8:9] offset:3072
	global_load_dwordx4 v[22:25], v15, s[8:9]
	s_nop 0
	global_load_dwordx4 v[26:29], v26, s[8:9]
	v_or_b32_e32 v15, 0x1800, v14
	v_or_b32_e32 v14, 0x1c00, v14
	s_add_u32 s26, s10, s26
	v_lshlrev_b32_e32 v34, 3, v118
	global_load_dwordx4 v[30:33], v15, s[8:9]
	global_load_dwordx4 v[36:39], v14, s[8:9]
	s_addc_u32 s27, s11, s27
	global_load_dwordx2 v[14:15], v34, s[28:29]
	global_load_dwordx2 v[40:41], v34, s[28:29] offset:512
	global_load_dwordx2 v[42:43], v34, s[28:29] offset:1024
	global_load_dwordx2 v[44:45], v34, s[28:29] offset:1536
	global_load_dwordx2 v[46:47], v34, s[28:29] offset:2048
	global_load_dwordx2 v[48:49], v34, s[28:29] offset:2560
	global_load_dwordx2 v[50:51], v34, s[28:29] offset:3072
	global_load_dwordx2 v[52:53], v34, s[28:29] offset:3584
	global_load_dwordx2 v[54:55], v34, s[26:27]
	global_load_dwordx2 v[56:57], v34, s[26:27] offset:512
	global_load_dwordx2 v[58:59], v34, s[26:27] offset:1024
	global_load_dwordx2 v[60:61], v34, s[26:27] offset:1536
	global_load_dwordx2 v[62:63], v34, s[26:27] offset:2048
	global_load_dwordx2 v[64:65], v34, s[26:27] offset:2560
	global_load_dwordx2 v[66:67], v34, s[26:27] offset:3072
	global_load_dwordx2 v[68:69], v34, s[26:27] offset:3584
	v_and_b32_e32 v70, 64, v213
	v_add_u32_e32 v70, 64, v70
	v_xor_b32_e32 v71, 1, v213
	v_cmp_lt_i32_e32 vcc, v71, v70
	v_lshl_add_u64 v[72:73], s[16:17], 0, v[34:35]
	s_nop 0
	v_cndmask_b32_e32 v71, v213, v71, vcc
	v_lshlrev_b32_e32 v119, 2, v71
	v_xor_b32_e32 v71, 2, v213
	v_cmp_lt_i32_e32 vcc, v71, v70
	s_nop 1
	v_cndmask_b32_e32 v71, v213, v71, vcc
	v_lshlrev_b32_e32 v120, 2, v71
	v_xor_b32_e32 v71, 4, v213
	v_cmp_lt_i32_e32 vcc, v71, v70
	s_nop 1
	v_cndmask_b32_e32 v71, v213, v71, vcc
	v_lshlrev_b32_e32 v121, 2, v71
	v_xor_b32_e32 v71, 8, v213
	v_cmp_lt_i32_e32 vcc, v71, v70
	s_nop 1
	v_cndmask_b32_e32 v71, v213, v71, vcc
	v_lshlrev_b32_e32 v122, 2, v71
	v_xor_b32_e32 v71, 16, v213
	v_cmp_lt_i32_e32 vcc, v71, v70
	s_nop 1
	v_cndmask_b32_e32 v71, v213, v71, vcc
	v_lshlrev_b32_e32 v123, 2, v71
	v_xor_b32_e32 v71, 32, v213
	v_cmp_lt_i32_e32 vcc, v71, v70
	s_nop 1
	v_cndmask_b32_e32 v70, v213, v71, vcc
	v_lshlrev_b32_e32 v124, 2, v70
	v_lshl_add_u64 v[70:71], s[10:11], 0, v[34:35]
	v_mov_b32_e32 v34, v35
	v_mov_b64_e32 v[74:75], v[34:35]
	v_mov_b64_e32 v[76:77], v[34:35]
	v_mov_b64_e32 v[78:79], v[34:35]
	v_mov_b64_e32 v[80:81], v[34:35]
	v_mov_b64_e32 v[82:83], v[34:35]
	v_mov_b64_e32 v[84:85], v[34:35]
	v_mov_b64_e32 v[86:87], v[34:35]
	v_mov_b64_e32 v[88:89], v[34:35]
	v_mov_b64_e32 v[90:91], v[34:35]
	v_mov_b64_e32 v[92:93], v[34:35]
	v_mov_b64_e32 v[94:95], v[34:35]
	v_mov_b64_e32 v[96:97], v[34:35]
	v_mov_b64_e32 v[98:99], v[34:35]
	v_mov_b64_e32 v[100:101], v[34:35]
	v_mov_b64_e32 v[102:103], v[34:35]
	v_mov_b64_e32 v[104:105], v[34:35]
	s_waitcnt vmcnt(0)
	s_branch .LBB0_1578

.LBB0_1577:
	s_waitcnt vmcnt(8)
	s_and_b64 vcc, exec, s[28:29]
	s_cbranch_vccnz .LBB0_1587

.LBB0_1580:
	v_and_b32_e32 v131, 0xffff0000, v40
	v_and_b32_e32 v130, 0xffff0000, v14
	v_and_b32_e32 v135, 0xffff0000, v41
	v_and_b32_e32 v134, 0xffff0000, v15
	v_lshlrev_b32_e32 v129, 16, v40
	v_lshlrev_b32_e32 v128, 16, v14
	v_lshlrev_b32_e32 v133, 16, v41
	v_lshlrev_b32_e32 v132, 16, v15
	v_pk_mul_f32 v[136:137], v[130:131], v[130:131]
	v_pk_mul_f32 v[138:139], v[134:135], v[134:135]
	v_pk_fma_f32 v[136:137], v[128:129], v[128:129], v[136:137]
	v_pk_fma_f32 v[138:139], v[132:133], v[132:133], v[138:139]
	v_and_b32_e32 v141, 0xffff0000, v43
	v_and_b32_e32 v140, 0xffff0000, v42
	v_lshlrev_b32_e32 v116, 16, v44
	v_and_b32_e32 v117, 0xffff0000, v44
	v_lshlrev_b32_e32 v112, 16, v46
	v_pk_add_f32 v[136:137], v[136:137], v[138:139]
	v_lshlrev_b32_e32 v139, 16, v43
	v_lshlrev_b32_e32 v138, 16, v42
	v_pk_mul_f32 v[142:143], v[140:141], v[140:141]
	v_lshlrev_b32_e32 v146, 16, v45
	v_pk_fma_f32 v[142:143], v[138:139], v[138:139], v[142:143]
	v_mul_f32_e32 v113, v116, v116
	v_mul_f32_e32 v145, v117, v117
	v_and_b32_e32 v147, 0xffff0000, v45
	v_mul_f32_e32 v34, v146, v146
	v_mov_b32_e32 v144, v112
	v_and_b32_e32 v125, 0xffff0000, v46
	v_lshlrev_b32_e32 v114, 16, v47
	v_and_b32_e32 v115, 0xffff0000, v47
	v_pk_add_f32 v[136:137], v[136:137], v[136:137] op_sel_hi:[0,1]
	v_pk_add_f32 v[142:143], v[142:143], v[142:143] op_sel_hi:[0,1]
	v_pk_fma_f32 v[148:149], v[146:147], v[146:147], v[34:35] op_sel_hi:[1,1,0]
	v_pk_add_f32 v[144:145], v[112:113], v[144:145]
	v_mul_f32_e32 v148, v125, v125
	v_mul_f32_e32 v142, v114, v114
	v_mul_f32_e32 v136, v115, v115
	v_mul_f32_e32 v150, v112, v112
	v_mov_b32_e32 v151, v145
	v_pk_add_f32 v[144:145], v[150:151], v[148:149]
	v_pk_add_f32 v[136:137], v[142:143], v[136:137]
	v_lshlrev_b32_e32 v110, 16, v50
	v_pk_add_f32 v[136:137], v[144:145], v[136:137]
	v_and_b32_e32 v145, 0xffff0000, v49
	v_and_b32_e32 v144, 0xffff0000, v48
	v_and_b32_e32 v111, 0xffff0000, v50
	s_waitcnt lgkmcnt(0)
	v_lshlrev_b32_e32 v106, 16, v52
	v_lshlrev_b32_e32 v143, 16, v49
	v_lshlrev_b32_e32 v142, 16, v48
	v_pk_mul_f32 v[148:149], v[144:145], v[144:145]
	v_lshlrev_b32_e32 v152, 16, v51
	v_pk_fma_f32 v[148:149], v[142:143], v[142:143], v[148:149]
	v_mul_f32_e32 v107, v110, v110
	v_mul_f32_e32 v151, v111, v111
	v_and_b32_e32 v153, 0xffff0000, v51
	v_mul_f32_e32 v34, v152, v152
	v_mov_b32_e32 v150, v106
	v_and_b32_e32 v183, 0xffff0000, v52
	v_lshlrev_b32_e32 v108, 16, v53
	v_and_b32_e32 v109, 0xffff0000, v53
	v_pk_add_f32 v[136:137], v[136:137], v[136:137] op_sel_hi:[0,1]
	v_pk_add_f32 v[148:149], v[148:149], v[148:149] op_sel_hi:[0,1]
	v_pk_fma_f32 v[154:155], v[152:153], v[152:153], v[34:35] op_sel_hi:[1,1,0]
	v_pk_add_f32 v[150:151], v[106:107], v[150:151]
	v_mul_f32_e32 v154, v183, v183
	v_mul_f32_e32 v148, v108, v108
	v_mul_f32_e32 v136, v109, v109
	v_mul_f32_e32 v156, v106, v106
	v_mov_b32_e32 v157, v151
	v_pk_add_f32 v[150:151], v[156:157], v[154:155]
	v_pk_add_f32 v[136:137], v[148:149], v[136:137]
	v_mov_b32_e32 v187, v130
	v_pk_add_f32 v[136:137], v[150:151], v[136:137]
	v_lshlrev_b32_e32 v126, 16, v54
	v_add_f32_e32 v34, v136, v137
	ds_bpermute_b32 v107, v119, v34
	v_and_b32_e32 v127, 0xffff0000, v54
	v_lshlrev_b32_e32 v136, 16, v55
	v_and_b32_e32 v137, 0xffff0000, v55
	v_lshlrev_b32_e32 v150, 16, v57
	s_waitcnt lgkmcnt(0)
	v_add_f32_e32 v34, v34, v107
	ds_bpermute_b32 v107, v120, v34
	v_and_b32_e32 v151, 0xffff0000, v57
	v_mov_b32_e32 v130, v129
	s_ashr_i32 s13, s12, 31
	v_lshlrev_b32_e32 v148, 16, v56
	s_waitcnt lgkmcnt(0)
	v_add_f32_e32 v34, v34, v107
	ds_bpermute_b32 v107, v121, v34
	v_and_b32_e32 v149, 0xffff0000, v56
	v_lshlrev_b32_e32 v154, 16, v58
	v_and_b32_e32 v155, 0xffff0000, v58
	v_lshlrev_b32_e32 v156, 16, v59
	s_waitcnt lgkmcnt(0)
	v_add_f32_e32 v34, v34, v107
	ds_bpermute_b32 v107, v122, v34
	v_and_b32_e32 v157, 0xffff0000, v59
	v_lshlrev_b32_e32 v158, 16, v60
	v_and_b32_e32 v159, 0xffff0000, v60
	v_lshlrev_b32_e32 v160, 16, v61
	s_waitcnt lgkmcnt(0)
	v_add_f32_e32 v34, v34, v107
	ds_bpermute_b32 v107, v123, v34
	v_and_b32_e32 v161, 0xffff0000, v61
	v_lshlrev_b32_e32 v162, 16, v62
	v_and_b32_e32 v163, 0xffff0000, v62
	v_lshlrev_b32_e32 v164, 16, v63
	s_waitcnt lgkmcnt(0)
	v_add_f32_e32 v34, v34, v107
	ds_bpermute_b32 v107, v124, v34
	v_and_b32_e32 v165, 0xffff0000, v63
	v_lshlrev_b32_e32 v166, 16, v64
	v_and_b32_e32 v167, 0xffff0000, v64
	v_lshlrev_b32_e32 v168, 16, v65
	s_waitcnt lgkmcnt(0)
	v_add_f32_e32 v34, v34, v107
	v_fmamk_f32 v34, v34, 0x3a000000, v209
	v_mul_f32_e32 v107, 0x4f800000, v34
	v_cmp_gt_f32_e32 vcc, s33, v34
	v_and_b32_e32 v169, 0xffff0000, v65
	v_lshlrev_b32_e32 v170, 16, v66
	v_cndmask_b32_e32 v34, v34, v107, vcc
	v_sqrt_f32_e32 v107, v34
	v_and_b32_e32 v171, 0xffff0000, v66
	v_lshlrev_b32_e32 v172, 16, v67
	v_and_b32_e32 v173, 0xffff0000, v67
	v_add_u32_e32 v113, -1, v107
	v_fma_f32 v175, -v113, v107, v34
	v_cmp_ge_f32_e64 s[44:45], 0, v175
	v_add_u32_e32 v175, 1, v107
	v_lshlrev_b32_e32 v174, 16, v68
	v_cndmask_b32_e64 v113, v107, v113, s[44:45]
	v_fma_f32 v107, -v175, v107, v34
	v_cmp_lt_f32_e64 s[44:45], 0, v107
	v_lshlrev_b32_e32 v176, 16, v69
	v_and_b32_e32 v177, 0xffff0000, v69
	v_cndmask_b32_e64 v107, v113, v175, s[44:45]
	v_mul_f32_e32 v113, 0x37800000, v107
	v_cndmask_b32_e32 v107, v107, v113, vcc
	v_cmp_class_f32_e32 vcc, v34, v210
	v_and_b32_e32 v175, 0xffff0000, v68
	s_nop 0
	v_cndmask_b32_e32 v34, v107, v34, vcc
	v_div_scale_f32 v107, s[16:17], v34, v34, 1.0
	v_rcp_f32_e32 v113, v107
	s_lshl_b64 s[16:17], s[12:13], 12
	v_fma_f32 v184, -v107, v113, 1.0
	v_fmac_f32_e32 v113, v184, v113
	v_div_scale_f32 v184, vcc, 1.0, v34, 1.0
	v_mul_f32_e32 v185, v184, v113
	v_fma_f32 v186, -v107, v185, v184
	v_fmac_f32_e32 v185, v186, v113
	v_fma_f32 v107, -v107, v185, v184
	v_div_fmas_f32 v107, v107, v113, v185
	v_div_fixup_f32 v34, v107, v34, 1.0
	v_mov_b32_e32 v184, v132
	v_mov_b32_e32 v185, v134
	v_mov_b32_e32 v186, v128
	v_mov_b32_e32 v134, v133
	v_pk_mul_f32 v[184:185], v[34:35], v[184:185] op_sel_hi:[0,1]
	v_pk_mul_f32 v[186:187], v[34:35], v[186:187] op_sel_hi:[0,1]
	v_pk_mul_f32 v[132:133], v[34:35], v[134:135] op_sel_hi:[0,1]
	v_pk_fma_f32 v[126:127], v[2:3], v[186:187], v[126:127]
	v_pk_fma_f32 v[136:137], v[4:5], v[184:185], v[136:137]
	v_pk_mul_f32 v[128:129], v[34:35], v[130:131] op_sel_hi:[0,1]
	v_pk_fma_f32 v[130:131], v[8:9], v[132:133], v[150:151]
	v_mov_b32_e32 v132, v139
	v_mov_b32_e32 v133, v141
	v_mov_b32_e32 v139, v140
	v_mov_b32_e32 v113, v125
	v_mov_b32_e32 v140, v143
	v_mov_b32_e32 v141, v145
	v_mov_b32_e32 v143, v144
	v_mov_b32_e32 v107, v183
	v_pk_mul_f32 v[132:133], v[34:35], v[132:133] op_sel_hi:[0,1]
	v_pk_mul_f32 v[134:135], v[34:35], v[138:139] op_sel_hi:[0,1]
	v_pk_mul_f32 v[138:139], v[34:35], v[146:147] op_sel_hi:[0,1]
	v_pk_mul_f32 v[116:117], v[34:35], v[116:117] op_sel_hi:[0,1]
	v_pk_mul_f32 v[114:115], v[34:35], v[114:115] op_sel_hi:[0,1]
	v_pk_mul_f32 v[112:113], v[34:35], v[112:113] op_sel_hi:[0,1]
	v_pk_mul_f32 v[140:141], v[34:35], v[140:141] op_sel_hi:[0,1]
	v_pk_mul_f32 v[142:143], v[34:35], v[142:143] op_sel_hi:[0,1]
	v_pk_mul_f32 v[144:145], v[34:35], v[152:153] op_sel_hi:[0,1]
	v_pk_mul_f32 v[110:111], v[34:35], v[110:111] op_sel_hi:[0,1]
	v_pk_mul_f32 v[108:109], v[34:35], v[108:109] op_sel_hi:[0,1]
	v_pk_mul_f32 v[106:107], v[34:35], v[106:107] op_sel_hi:[0,1]
	v_mul_f32_e32 v34, v127, v127
	v_mul_f32_e32 v125, v137, v137
	v_fmac_f32_e32 v34, v126, v126
	v_fmac_f32_e32 v125, v136, v136
	v_add_f32_e32 v34, v34, v125
	v_and_b32_sdwa v125, v136, v206 dst_sel:DWORD dst_unused:UNUSED_PAD src0_sel:WORD_1 src1_sel:DWORD
	v_and_b32_sdwa v146, v126, v206 dst_sel:DWORD dst_unused:UNUSED_PAD src0_sel:WORD_1 src1_sel:DWORD
	v_add3_u32 v126, v126, v146, s69
	v_add3_u32 v125, v136, v125, s69
	v_and_b32_sdwa v136, v137, v206 dst_sel:DWORD dst_unused:UNUSED_PAD src0_sel:WORD_1 src1_sel:DWORD
	v_and_b32_sdwa v146, v127, v206 dst_sel:DWORD dst_unused:UNUSED_PAD src0_sel:WORD_1 src1_sel:DWORD
	v_add3_u32 v136, v137, v136, s69
	v_add3_u32 v127, v127, v146, s69
	v_and_b32_e32 v136, 0xffff0000, v136
	v_and_b32_e32 v137, 0xffff0000, v127
	v_pk_fma_f32 v[128:129], v[6:7], v[128:129], v[148:149]
	v_or_b32_sdwa v127, v136, v125 dst_sel:DWORD dst_unused:UNUSED_PAD src0_sel:DWORD src1_sel:WORD_1
	v_or_b32_sdwa v126, v137, v126 dst_sel:DWORD dst_unused:UNUSED_PAD src0_sel:DWORD src1_sel:WORD_1
	v_lshl_add_u64 v[136:137], v[70:71], 0, s[16:17]
	global_store_dwordx2 v[136:137], v[126:127], off
	v_mul_f32_e32 v125, v129, v129
	v_mul_f32_e32 v126, v131, v131
	v_fmac_f32_e32 v125, v128, v128
	v_fmac_f32_e32 v126, v130, v130
	v_add_f32_e32 v125, v125, v126
	v_and_b32_sdwa v126, v128, v206 dst_sel:DWORD dst_unused:UNUSED_PAD src0_sel:WORD_1 src1_sel:DWORD
	v_add3_u32 v126, v128, v126, s69
	v_and_b32_sdwa v127, v131, v206 dst_sel:DWORD dst_unused:UNUSED_PAD src0_sel:WORD_1 src1_sel:DWORD
	v_and_b32_sdwa v128, v129, v206 dst_sel:DWORD dst_unused:UNUSED_PAD src0_sel:WORD_1 src1_sel:DWORD
	v_add_f32_e32 v34, v34, v125
	v_and_b32_sdwa v125, v130, v206 dst_sel:DWORD dst_unused:UNUSED_PAD src0_sel:WORD_1 src1_sel:DWORD
	v_add3_u32 v127, v131, v127, s69
	v_add3_u32 v128, v129, v128, s69
	v_add3_u32 v125, v130, v125, s69
	v_and_b32_e32 v127, 0xffff0000, v127
	v_and_b32_e32 v128, 0xffff0000, v128
	v_pk_fma_f32 v[134:135], v[10:11], v[134:135], v[154:155]
	v_pk_fma_f32 v[132:133], v[12:13], v[132:133], v[156:157]
	v_or_b32_sdwa v127, v127, v125 dst_sel:DWORD dst_unused:UNUSED_PAD src0_sel:DWORD src1_sel:WORD_1
	v_or_b32_sdwa v126, v128, v126 dst_sel:DWORD dst_unused:UNUSED_PAD src0_sel:DWORD src1_sel:WORD_1
	global_store_dwordx2 v[136:137], v[126:127], off offset:512
	v_mul_f32_e32 v125, v135, v135
	v_mul_f32_e32 v126, v133, v133
	v_fmac_f32_e32 v125, v134, v134
	v_fmac_f32_e32 v126, v132, v132
	v_add_f32_e32 v125, v125, v126
	v_and_b32_sdwa v127, v133, v206 dst_sel:DWORD dst_unused:UNUSED_PAD src0_sel:WORD_1 src1_sel:DWORD
	v_and_b32_sdwa v128, v135, v206 dst_sel:DWORD dst_unused:UNUSED_PAD src0_sel:WORD_1 src1_sel:DWORD
	v_add_f32_e32 v34, v125, v34
	v_and_b32_sdwa v125, v132, v206 dst_sel:DWORD dst_unused:UNUSED_PAD src0_sel:WORD_1 src1_sel:DWORD
	v_and_b32_sdwa v126, v134, v206 dst_sel:DWORD dst_unused:UNUSED_PAD src0_sel:WORD_1 src1_sel:DWORD
	v_add3_u32 v127, v133, v127, s69
	v_add3_u32 v128, v135, v128, s69
	v_add3_u32 v126, v134, v126, s69
	v_add3_u32 v125, v132, v125, s69
	v_and_b32_e32 v127, 0xffff0000, v127
	v_and_b32_e32 v128, 0xffff0000, v128
	v_pk_fma_f32 v[116:117], v[18:19], v[116:117], v[158:159]
	v_pk_fma_f32 v[138:139], v[20:21], v[138:139], v[160:161]
	v_or_b32_sdwa v127, v127, v125 dst_sel:DWORD dst_unused:UNUSED_PAD src0_sel:DWORD src1_sel:WORD_1
	v_or_b32_sdwa v126, v128, v126 dst_sel:DWORD dst_unused:UNUSED_PAD src0_sel:DWORD src1_sel:WORD_1
	global_store_dwordx2 v[136:137], v[126:127], off offset:1024
	v_mul_f32_e32 v125, v117, v117
	v_mul_f32_e32 v126, v139, v139
	v_fmac_f32_e32 v125, v116, v116
	v_fmac_f32_e32 v126, v138, v138
	v_add_f32_e32 v125, v125, v126
	v_and_b32_sdwa v126, v116, v206 dst_sel:DWORD dst_unused:UNUSED_PAD src0_sel:WORD_1 src1_sel:DWORD
	v_add3_u32 v116, v116, v126, s69
	v_and_b32_sdwa v126, v139, v206 dst_sel:DWORD dst_unused:UNUSED_PAD src0_sel:WORD_1 src1_sel:DWORD
	v_and_b32_sdwa v127, v117, v206 dst_sel:DWORD dst_unused:UNUSED_PAD src0_sel:WORD_1 src1_sel:DWORD
	v_add_f32_e32 v34, v125, v34
	v_and_b32_sdwa v125, v138, v206 dst_sel:DWORD dst_unused:UNUSED_PAD src0_sel:WORD_1 src1_sel:DWORD
	v_add3_u32 v126, v139, v126, s69
	v_add3_u32 v117, v117, v127, s69
	v_add3_u32 v125, v138, v125, s69
	v_and_b32_e32 v126, 0xffff0000, v126
	v_and_b32_e32 v127, 0xffff0000, v117
	v_pk_fma_f32 v[112:113], v[22:23], v[112:113], v[162:163]
	v_pk_fma_f32 v[114:115], v[24:25], v[114:115], v[164:165]
	v_or_b32_sdwa v117, v126, v125 dst_sel:DWORD dst_unused:UNUSED_PAD src0_sel:DWORD src1_sel:WORD_1
	v_or_b32_sdwa v116, v127, v116 dst_sel:DWORD dst_unused:UNUSED_PAD src0_sel:DWORD src1_sel:WORD_1
	global_store_dwordx2 v[136:137], v[116:117], off offset:1536
	v_mul_f32_e32 v116, v113, v113
	v_mul_f32_e32 v117, v115, v115
	v_fmac_f32_e32 v116, v112, v112
	v_fmac_f32_e32 v117, v114, v114
	v_add_f32_e32 v116, v116, v117
	v_add_f32_e32 v34, v116, v34
	v_and_b32_sdwa v116, v114, v206 dst_sel:DWORD dst_unused:UNUSED_PAD src0_sel:WORD_1 src1_sel:DWORD
	v_and_b32_sdwa v117, v112, v206 dst_sel:DWORD dst_unused:UNUSED_PAD src0_sel:WORD_1 src1_sel:DWORD
	v_add3_u32 v112, v112, v117, s69
	v_add3_u32 v114, v114, v116, s69
	v_and_b32_sdwa v116, v115, v206 dst_sel:DWORD dst_unused:UNUSED_PAD src0_sel:WORD_1 src1_sel:DWORD
	v_and_b32_sdwa v117, v113, v206 dst_sel:DWORD dst_unused:UNUSED_PAD src0_sel:WORD_1 src1_sel:DWORD
	v_add3_u32 v115, v115, v116, s69
	v_add3_u32 v113, v113, v117, s69
	v_and_b32_e32 v115, 0xffff0000, v115
	v_and_b32_e32 v116, 0xffff0000, v113
	v_pk_fma_f32 v[142:143], v[26:27], v[142:143], v[166:167]
	v_pk_fma_f32 v[140:141], v[28:29], v[140:141], v[168:169]
	v_or_b32_sdwa v113, v115, v114 dst_sel:DWORD dst_unused:UNUSED_PAD src0_sel:DWORD src1_sel:WORD_1
	v_or_b32_sdwa v112, v116, v112 dst_sel:DWORD dst_unused:UNUSED_PAD src0_sel:DWORD src1_sel:WORD_1
	global_store_dwordx2 v[136:137], v[112:113], off offset:2048
	v_mul_f32_e32 v112, v143, v143
	v_mul_f32_e32 v113, v141, v141
	v_fmac_f32_e32 v112, v142, v142
	v_fmac_f32_e32 v113, v140, v140
	v_add_f32_e32 v112, v112, v113
	v_and_b32_sdwa v113, v142, v206 dst_sel:DWORD dst_unused:UNUSED_PAD src0_sel:WORD_1 src1_sel:DWORD
	v_add3_u32 v114, v142, v113, s69
	v_and_b32_sdwa v113, v141, v206 dst_sel:DWORD dst_unused:UNUSED_PAD src0_sel:WORD_1 src1_sel:DWORD
	v_and_b32_sdwa v115, v143, v206 dst_sel:DWORD dst_unused:UNUSED_PAD src0_sel:WORD_1 src1_sel:DWORD
	v_add_f32_e32 v34, v112, v34
	v_and_b32_sdwa v112, v140, v206 dst_sel:DWORD dst_unused:UNUSED_PAD src0_sel:WORD_1 src1_sel:DWORD
	v_add3_u32 v113, v141, v113, s69
	v_add3_u32 v115, v143, v115, s69
	v_add3_u32 v112, v140, v112, s69
	v_and_b32_e32 v113, 0xffff0000, v113
	v_and_b32_e32 v115, 0xffff0000, v115
	v_pk_fma_f32 v[110:111], v[30:31], v[110:111], v[170:171]
	v_pk_fma_f32 v[144:145], v[32:33], v[144:145], v[172:173]
	v_or_b32_sdwa v113, v113, v112 dst_sel:DWORD dst_unused:UNUSED_PAD src0_sel:DWORD src1_sel:WORD_1
	v_or_b32_sdwa v112, v115, v114 dst_sel:DWORD dst_unused:UNUSED_PAD src0_sel:DWORD src1_sel:WORD_1
	v_pk_fma_f32 v[106:107], v[36:37], v[106:107], v[174:175]
	v_pk_fma_f32 v[108:109], v[38:39], v[108:109], v[176:177]
	global_store_dwordx2 v[136:137], v[112:113], off offset:2560
	v_mul_f32_e32 v112, v111, v111
	v_mul_f32_e32 v113, v145, v145
	v_fmac_f32_e32 v112, v110, v110
	v_fmac_f32_e32 v113, v144, v144
	v_mul_f32_e32 v114, v107, v107
	v_mul_f32_e32 v115, v109, v109
	v_add_f32_e32 v112, v112, v113
	v_fmac_f32_e32 v114, v106, v106
	v_fmac_f32_e32 v115, v108, v108
	v_add_f32_e32 v34, v112, v34
	v_add_f32_e32 v114, v114, v115
	v_add_f32_e32 v34, v114, v34
	ds_bpermute_b32 v114, v119, v34
	v_and_b32_sdwa v113, v110, v206 dst_sel:DWORD dst_unused:UNUSED_PAD src0_sel:WORD_1 src1_sel:DWORD
	v_add3_u32 v110, v110, v113, s69
	v_and_b32_sdwa v113, v145, v206 dst_sel:DWORD dst_unused:UNUSED_PAD src0_sel:WORD_1 src1_sel:DWORD
	v_and_b32_sdwa v115, v111, v206 dst_sel:DWORD dst_unused:UNUSED_PAD src0_sel:WORD_1 src1_sel:DWORD
	s_waitcnt lgkmcnt(0)
	v_add_f32_e32 v34, v34, v114
	ds_bpermute_b32 v114, v120, v34
	v_and_b32_sdwa v112, v144, v206 dst_sel:DWORD dst_unused:UNUSED_PAD src0_sel:WORD_1 src1_sel:DWORD
	v_add3_u32 v113, v145, v113, s69
	v_add3_u32 v111, v111, v115, s69
	v_add3_u32 v112, v144, v112, s69
	s_waitcnt lgkmcnt(0)
	v_add_f32_e32 v34, v34, v114
	ds_bpermute_b32 v114, v121, v34
	v_and_b32_e32 v113, 0xffff0000, v113
	v_and_b32_e32 v115, 0xffff0000, v111
	v_or_b32_sdwa v111, v113, v112 dst_sel:DWORD dst_unused:UNUSED_PAD src0_sel:DWORD src1_sel:WORD_1
	v_or_b32_sdwa v110, v115, v110 dst_sel:DWORD dst_unused:UNUSED_PAD src0_sel:DWORD src1_sel:WORD_1
	s_waitcnt lgkmcnt(0)
	v_add_f32_e32 v34, v34, v114
	global_store_dwordx2 v[136:137], v[110:111], off offset:3072
	ds_bpermute_b32 v111, v122, v34
	v_and_b32_sdwa v110, v108, v206 dst_sel:DWORD dst_unused:UNUSED_PAD src0_sel:WORD_1 src1_sel:DWORD
	v_add3_u32 v108, v108, v110, s69
	v_and_b32_sdwa v112, v106, v206 dst_sel:DWORD dst_unused:UNUSED_PAD src0_sel:WORD_1 src1_sel:DWORD
	v_add3_u32 v112, v106, v112, s69
	s_waitcnt lgkmcnt(0)
	v_add_f32_e32 v34, v34, v111
	ds_bpermute_b32 v110, v123, v34
	v_and_b32_sdwa v106, v109, v206 dst_sel:DWORD dst_unused:UNUSED_PAD src0_sel:WORD_1 src1_sel:DWORD
	v_add3_u32 v106, v109, v106, s69
	v_and_b32_e32 v109, 0xffff0000, v106
	v_and_b32_sdwa v111, v107, v206 dst_sel:DWORD dst_unused:UNUSED_PAD src0_sel:WORD_1 src1_sel:DWORD
	s_waitcnt lgkmcnt(0)
	v_add_f32_e32 v34, v34, v110
	ds_bpermute_b32 v106, v124, v34
	v_add3_u32 v107, v107, v111, s69
	v_and_b32_e32 v107, 0xffff0000, v107
	v_or_b32_sdwa v109, v109, v108 dst_sel:DWORD dst_unused:UNUSED_PAD src0_sel:DWORD src1_sel:WORD_1
	v_or_b32_sdwa v108, v107, v112 dst_sel:DWORD dst_unused:UNUSED_PAD src0_sel:DWORD src1_sel:WORD_1
	global_store_dwordx2 v[136:137], v[108:109], off offset:3584
	s_and_saveexec_b64 s[34:35], s[42:43]
	s_cbranch_execz .LBB0_1582
	s_waitcnt lgkmcnt(0)
	v_add_f32_e32 v34, v34, v106
	v_fmamk_f32 v34, v34, 0x3a000000, v209
	v_mul_f32_e32 v106, 0x4f800000, v34
	v_cmp_gt_f32_e32 vcc, s33, v34
	s_nop 1
	v_cndmask_b32_e32 v34, v34, v106, vcc
	v_sqrt_f32_e32 v106, v34
	s_nop 0
	v_add_u32_e32 v107, -1, v106
	v_fma_f32 v109, -v107, v106, v34
	v_add_u32_e32 v108, 1, v106
	v_cmp_ge_f32_e64 s[44:45], 0, v109
	s_nop 1
	v_cndmask_b32_e64 v107, v106, v107, s[44:45]
	v_fma_f32 v106, -v108, v106, v34
	v_cmp_lt_f32_e64 s[44:45], 0, v106
	s_nop 1
	v_cndmask_b32_e64 v106, v107, v108, s[44:45]
	v_mul_f32_e32 v107, 0x37800000, v106
	v_cndmask_b32_e32 v106, v106, v107, vcc
	v_cmp_class_f32_e32 vcc, v34, v210
	s_nop 1
	v_cndmask_b32_e32 v34, v106, v34, vcc
	v_div_scale_f32 v106, s[16:17], v34, v34, 1.0
	v_rcp_f32_e32 v107, v106
	s_lshl_b64 s[16:17], s[12:13], 2
	s_add_u32 s16, s6, s16
	s_addc_u32 s17, s14, s17
	v_fma_f32 v108, -v106, v107, 1.0
	v_fmac_f32_e32 v107, v108, v107
	v_div_scale_f32 v108, vcc, 1.0, v34, 1.0
	v_mul_f32_e32 v109, v108, v107
	v_fma_f32 v110, -v106, v109, v108
	v_fmac_f32_e32 v109, v110, v107
	v_fma_f32 v106, -v106, v109, v108
	v_div_fmas_f32 v106, v106, v107, v109
	v_div_fixup_f32 v34, v106, v34, 1.0
	global_store_dword v35, v34, s[16:17]
	s_or_b64 exec, exec, s[34:35]
	s_andn2_b64 vcc, exec, s[28:29]
	s_mov_b64 s[28:29], -1
	s_cbranch_vccnz .LBB0_1577
	s_branch .LBB0_1583

.LBB0_1583:
	s_waitcnt vmcnt(8)
	v_readlane_b32 s11, v252, 23
	s_add_i32 s12, s11, s12
	s_cmpk_gt_i32 s12, 0x1fff
	s_cbranch_scc1 .LBB0_1585
	s_ashr_i32 s13, s12, 31
	s_lshl_b64 s[12:13], s[12:13], 12
	v_lshl_add_u64 v[52:53], v[72:73], 0, s[12:13]
	v_lshl_add_u64 v[68:69], v[70:71], 0, s[12:13]
	global_load_dwordx2 v[14:15], v[52:53], off
	global_load_dwordx2 v[40:41], v[52:53], off offset:512
	global_load_dwordx2 v[42:43], v[52:53], off offset:1024
	global_load_dwordx2 v[44:45], v[52:53], off offset:1536
	global_load_dwordx2 v[46:47], v[52:53], off offset:2048
	global_load_dwordx2 v[48:49], v[52:53], off offset:2560
	global_load_dwordx2 v[50:51], v[52:53], off offset:3072
	s_nop 0
	global_load_dwordx2 v[52:53], v[52:53], off offset:3584
	s_nop 0
	global_load_dwordx2 v[54:55], v[68:69], off
	global_load_dwordx2 v[56:57], v[68:69], off offset:512
	global_load_dwordx2 v[58:59], v[68:69], off offset:1024
	global_load_dwordx2 v[60:61], v[68:69], off offset:1536
	global_load_dwordx2 v[62:63], v[68:69], off offset:2048
	global_load_dwordx2 v[64:65], v[68:69], off offset:2560
	global_load_dwordx2 v[66:67], v[68:69], off offset:3072
	s_nop 0
	global_load_dwordx2 v[68:69], v[68:69], off offset:3584
